# converter stores non-temporal (nt) so the converted weights do not displace the attention K/V working set in L2
# speedup vs baseline: 1.0275x; 1.0010x over previous
.Lcv_nomul_a:
	v_cvt_pk_bf16_f32 v112, v16, v20
	v_cvt_pk_bf16_f32 v113, v24, v28
	v_cvt_pk_bf16_f32 v114, v32, v36
	v_cvt_pk_bf16_f32 v115, v40, v44
	v_cvt_pk_bf16_f32 v116, v17, v21
	v_cvt_pk_bf16_f32 v117, v25, v29
	v_cvt_pk_bf16_f32 v118, v33, v37
	v_cvt_pk_bf16_f32 v119, v41, v45
	v_cvt_pk_bf16_f32 v120, v18, v22
	v_cvt_pk_bf16_f32 v121, v26, v30
	v_cvt_pk_bf16_f32 v122, v34, v38
	v_cvt_pk_bf16_f32 v123, v42, v46
	v_cvt_pk_bf16_f32 v124, v19, v23
	v_cvt_pk_bf16_f32 v125, v27, v31
	v_cvt_pk_bf16_f32 v126, v35, v39
	v_cvt_pk_bf16_f32 v127, v43, v47
	global_store_dwordx4 v5, v[112:115], s[22:23] nt
	s_add_u32 s22, s22, 0x1000
	s_addc_u32 s23, s23, 0
	global_store_dwordx4 v5, v[116:119], s[22:23] nt
	s_add_u32 s22, s22, 0x1000
	s_addc_u32 s23, s23, 0
	global_store_dwordx4 v5, v[120:123], s[22:23] nt
	s_add_u32 s22, s22, 0x1000
	s_addc_u32 s23, s23, 0
	global_store_dwordx4 v5, v[124:127], s[22:23] nt
	s_add_u32 s7, s46, 0x400
	s_sub_u32 s47, s7, s59
	s_cmp_lt_u32 s47, 0x400
	s_cselect_b32 s47, 0x2800, 0
	s_add_u32 s7, s7, s47
	s_cmp_lt_u32 s46, s58
	s_cbranch_scc0 .Lcv_done
	s_cmp_lt_u32 s7, s58
	s_cbranch_scc0 .Lcv_noa
	s_mul_hi_u32 s9, s7, 0x66666667
	s_lshr_b32 s9, s9, 12
	s_mul_i32 s10, s9, 0x2800
	s_sub_u32 s10, s7, s10
	s_sub_u32 s9, 3, s9
	s_cmp_lt_u32 s10, 0x2000
	s_cselect_b64 s[12:13], -1, 0
	s_cselect_b32 s11, 0, 0x2000
	s_cselect_b32 s14, 7, 5
	s_cselect_b32 s15, 15, 13
	s_cselect_b32 s48, 26, 24
	s_cselect_b32 s17, 25, 23
	s_cselect_b32 s20, s4, s18
	s_cselect_b32 s21, s5, s19
	s_cselect_b32 s22, s40, s42
	s_cselect_b32 s23, s41, s43
	s_sub_u32 s10, s10, s11
	s_lshr_b32 s24, s10, 3
	s_lshr_b32 s25, s24, s14
	s_lshl_b32 s26, s25, s14
	s_sub_u32 s24, s24, s26
	s_and_b32 s26, s10, 1
	s_lshl_b32 s24, s24, 1
	s_or_b32 s24, s24, s26
	s_bfe_u32 s26, s10, 0x20001
	s_lshl_b32 s25, s25, 2
	s_or_b32 s25, s25, s26
	s_lshl_b32 s25, s25, 6
	s_lshl_b32 s24, s24, 5
	s_lshl_b32 s26, s9, s48
	s_lshl_b32 s27, s25, s15
	s_add_u32 s26, s26, s27
	s_lshl_b32 s27, s24, 2
	s_add_u32 s26, s26, s27
	s_add_u32 s20, s20, s26
	s_addc_u32 s21, s21, 0
	s_lshl_b32 s28, 1, s15
	s_lshl_b32 s26, s9, s17
	s_lshl_b32 s27, s24, 12
	s_add_u32 s26, s26, s27
	s_lshl_b32 s27, s25, 1
	s_add_u32 s26, s26, s27
	s_add_u32 s22, s22, s26
	s_addc_u32 s23, s23, 0
	s_lshl_b32 s26, s9, 13
	s_lshl_b32 s27, s25, 2
	s_add_u32 s26, s26, s27
	s_add_u32 s30, s2, s26
	s_addc_u32 s31, s3, 0
	v_cndmask_b32_e64 v6, v3, v2, s[12:13]
	global_load_dwordx4 v[48:51], v11, s[30:31]
	global_load_dwordx4 v[52:55], v11, s[30:31] offset:16
	global_load_dwordx4 v[16:19], v6, s[20:21] nt
	s_add_u32 s20, s20, s28
	s_addc_u32 s21, s21, 0
	global_load_dwordx4 v[20:23], v6, s[20:21] nt
	s_add_u32 s20, s20, s28
	s_addc_u32 s21, s21, 0
	global_load_dwordx4 v[24:27], v6, s[20:21] nt
	s_add_u32 s20, s20, s28
	s_addc_u32 s21, s21, 0
	global_load_dwordx4 v[28:31], v6, s[20:21] nt
	s_add_u32 s20, s20, s28
	s_addc_u32 s21, s21, 0
	global_load_dwordx4 v[32:35], v6, s[20:21] nt
	s_add_u32 s20, s20, s28
	s_addc_u32 s21, s21, 0
	global_load_dwordx4 v[36:39], v6, s[20:21] nt
	s_add_u32 s20, s20, s28
	s_addc_u32 s21, s21, 0
	global_load_dwordx4 v[40:43], v6, s[20:21] nt
	s_add_u32 s20, s20, s28
	s_addc_u32 s21, s21, 0
	global_load_dwordx4 v[44:47], v6, s[20:21] nt
	s_waitcnt vmcnt(14)
	s_branch .Lcv_procb

.Lcv_nomul_b:
	v_cvt_pk_bf16_f32 v112, v64, v68
	v_cvt_pk_bf16_f32 v113, v72, v76
	v_cvt_pk_bf16_f32 v114, v80, v84
	v_cvt_pk_bf16_f32 v115, v88, v92
	v_cvt_pk_bf16_f32 v116, v65, v69
	v_cvt_pk_bf16_f32 v117, v73, v77
	v_cvt_pk_bf16_f32 v118, v81, v85
	v_cvt_pk_bf16_f32 v119, v89, v93
	v_cvt_pk_bf16_f32 v120, v66, v70
	v_cvt_pk_bf16_f32 v121, v74, v78
	v_cvt_pk_bf16_f32 v122, v82, v86
	v_cvt_pk_bf16_f32 v123, v90, v94
	v_cvt_pk_bf16_f32 v124, v67, v71
	v_cvt_pk_bf16_f32 v125, v75, v79
	v_cvt_pk_bf16_f32 v126, v83, v87
	v_cvt_pk_bf16_f32 v127, v91, v95
	global_store_dwordx4 v5, v[112:115], s[34:35] nt
	s_add_u32 s34, s34, 0x1000
	s_addc_u32 s35, s35, 0
	global_store_dwordx4 v5, v[116:119], s[34:35] nt
	s_add_u32 s34, s34, 0x1000
	s_addc_u32 s35, s35, 0
	global_store_dwordx4 v5, v[120:123], s[34:35] nt
	s_add_u32 s34, s34, 0x1000
	s_addc_u32 s35, s35, 0
	global_store_dwordx4 v5, v[124:127], s[34:35] nt
	s_add_u32 s46, s7, 0x400
	s_sub_u32 s47, s46, s59
	s_cmp_lt_u32 s47, 0x400
	s_cselect_b32 s47, 0x2800, 0
	s_add_u32 s46, s46, s47
	s_cmp_lt_u32 s7, s58
	s_cbranch_scc0 .Lcv_done
	s_cmp_lt_u32 s46, s58
	s_cbranch_scc0 .Lcv_nob
	s_mul_hi_u32 s9, s46, 0x66666667
	s_lshr_b32 s9, s9, 12
	s_mul_i32 s10, s9, 0x2800
	s_sub_u32 s10, s46, s10
	s_sub_u32 s9, 3, s9
	s_cmp_lt_u32 s10, 0x2000
	s_cselect_b64 s[50:51], -1, 0
	s_cselect_b32 s11, 0, 0x2000
	s_cselect_b32 s14, 7, 5
	s_cselect_b32 s15, 15, 13
	s_cselect_b32 s48, 26, 24
	s_cselect_b32 s17, 25, 23
	s_cselect_b32 s38, s4, s18
	s_cselect_b32 s39, s5, s19
	s_cselect_b32 s34, s40, s42
	s_cselect_b32 s35, s41, s43
	s_sub_u32 s10, s10, s11
	s_lshr_b32 s24, s10, 3
	s_lshr_b32 s25, s24, s14
	s_lshl_b32 s26, s25, s14
	s_sub_u32 s24, s24, s26
	s_and_b32 s26, s10, 1
	s_lshl_b32 s24, s24, 1
	s_or_b32 s24, s24, s26
	s_bfe_u32 s26, s10, 0x20001
	s_lshl_b32 s25, s25, 2
	s_or_b32 s25, s25, s26
	s_lshl_b32 s25, s25, 6
	s_lshl_b32 s24, s24, 5
	s_lshl_b32 s26, s9, s48
	s_lshl_b32 s27, s25, s15
	s_add_u32 s26, s26, s27
	s_lshl_b32 s27, s24, 2
	s_add_u32 s26, s26, s27
	s_add_u32 s38, s38, s26
	s_addc_u32 s39, s39, 0
	s_lshl_b32 s29, 1, s15
	s_lshl_b32 s26, s9, s17
	s_lshl_b32 s27, s24, 12
	s_add_u32 s26, s26, s27
	s_lshl_b32 s27, s25, 1
	s_add_u32 s26, s26, s27
	s_add_u32 s34, s34, s26
	s_addc_u32 s35, s35, 0
	s_lshl_b32 s26, s9, 13
	s_lshl_b32 s27, s25, 2
	s_add_u32 s26, s26, s27
	s_add_u32 s56, s2, s26
	s_addc_u32 s57, s3, 0
	v_cndmask_b32_e64 v7, v3, v2, s[50:51]
	global_load_dwordx4 v[96:99], v11, s[56:57]
	global_load_dwordx4 v[100:103], v11, s[56:57] offset:16
	global_load_dwordx4 v[64:67], v7, s[38:39] nt
	s_add_u32 s38, s38, s29
	s_addc_u32 s39, s39, 0
	global_load_dwordx4 v[68:71], v7, s[38:39] nt
	s_add_u32 s38, s38, s29
	s_addc_u32 s39, s39, 0
	global_load_dwordx4 v[72:75], v7, s[38:39] nt
	s_add_u32 s38, s38, s29
	s_addc_u32 s39, s39, 0
	global_load_dwordx4 v[76:79], v7, s[38:39] nt
	s_add_u32 s38, s38, s29
	s_addc_u32 s39, s39, 0
	global_load_dwordx4 v[80:83], v7, s[38:39] nt
	s_add_u32 s38, s38, s29
	s_addc_u32 s39, s39, 0
	global_load_dwordx4 v[84:87], v7, s[38:39] nt
	s_add_u32 s38, s38, s29
	s_addc_u32 s39, s39, 0
	global_load_dwordx4 v[88:91], v7, s[38:39] nt
	s_add_u32 s38, s38, s29
	s_addc_u32 s39, s39, 0
	global_load_dwordx4 v[92:95], v7, s[38:39] nt
	s_waitcnt vmcnt(14)
	s_branch .Lcv_loop
